# scan compute waves: counted lgkmcnt waits (first MFMA group waits only for its 16 fragments, v_new arithmetic does not wait for the 8 KdT fragments just issued)
# speedup vs baseline: 1.0148x; 1.0008x over previous
.LBB0_723:
	s_andn2_b64 vcc, exec, s[46:47]
	s_cbranch_vccnz .LBB0_710
	s_mul_i32 s57, s57, 0xf000
	s_add_i32 s46, s57, 0
	v_mov_b32_e32 v36, s56
	v_add_u32_e32 v37, s46, v192
	ds_read_b32 v36, v36
	ds_read_b128 v[40:43], v37
	ds_read_b128 v[44:47], v37 offset:1024
	ds_read_b128 v[48:51], v37 offset:16384
	ds_read_b128 v[52:55], v37 offset:17408
	ds_read_b128 v[56:59], v37 offset:4096
	ds_read_b128 v[60:63], v37 offset:5120
	ds_read_b128 v[64:67], v37 offset:20480
	ds_read_b128 v[68:71], v37 offset:21504
	ds_read_b128 v[72:75], v37 offset:8192
	ds_read_b128 v[76:79], v37 offset:9216
	ds_read_b128 v[80:83], v37 offset:24576
	ds_read_b128 v[84:87], v37 offset:25600
	ds_read_b128 v[88:91], v37 offset:12288
	ds_read_b128 v[92:95], v37 offset:13312
	ds_read_b128 v[96:99], v37 offset:28672
	ds_read_b128 v[100:103], v37 offset:29696
	ds_read_b128 v[104:107], v37 offset:2048
	ds_read_b128 v[108:111], v37 offset:3072
	ds_read_b128 v[112:115], v37 offset:18432
	ds_read_b128 v[116:119], v37 offset:19456
	ds_read_b128 v[120:123], v37 offset:6144
	ds_read_b128 v[124:127], v37 offset:7168
	ds_read_b128 v[128:131], v37 offset:22528
	ds_read_b128 v[132:135], v37 offset:23552
	ds_read_b128 v[136:139], v37 offset:10240
	ds_read_b128 v[140:143], v37 offset:11264
	ds_read_b128 v[144:147], v37 offset:26624
	ds_read_b128 v[148:151], v37 offset:27648
	ds_read_b128 v[152:155], v37 offset:14336
	ds_read_b128 v[156:159], v37 offset:15360
	v_cvt_pk_bf16_f32 v168, v20, v21
	v_cvt_pk_bf16_f32 v169, v22, v23
	v_cvt_pk_bf16_f32 v170, v28, v29
	v_cvt_pk_bf16_f32 v171, v30, v31
	v_cvt_pk_bf16_f32 v172, v24, v25
	v_cvt_pk_bf16_f32 v173, v26, v27
	v_cvt_pk_bf16_f32 v174, v16, v17
	v_cvt_pk_bf16_f32 v175, v18, v19
	v_cvt_pk_bf16_f32 v176, v12, v13
	v_cvt_pk_bf16_f32 v177, v14, v15
	v_cvt_pk_bf16_f32 v178, v8, v9
	v_cvt_pk_bf16_f32 v179, v10, v11
	v_cvt_pk_bf16_f32 v180, v4, v5
	v_cvt_pk_bf16_f32 v181, v6, v7
	v_cvt_pk_bf16_f32 v182, v0, v1
	v_cvt_pk_bf16_f32 v183, v2, v3
	s_waitcnt lgkmcnt(14)
	v_mfma_f32_16x16x32_bf16 v[40:43], v[40:43], v[168:171], 0
	v_mfma_f32_16x16x32_bf16 v[56:59], v[56:59], v[168:171], 0
	v_mfma_f32_16x16x32_bf16 v[72:75], v[72:75], v[168:171], 0
	v_mfma_f32_16x16x32_bf16 v[88:91], v[88:91], v[168:171], 0
	v_mfma_f32_16x16x32_bf16 v[48:51], v[168:171], v[48:51], 0
	v_mfma_f32_16x16x32_bf16 v[64:67], v[168:171], v[64:67], 0
	v_mfma_f32_16x16x32_bf16 v[80:83], v[168:171], v[80:83], 0
	v_mfma_f32_16x16x32_bf16 v[96:99], v[168:171], v[96:99], 0
	v_mfma_f32_16x16x32_bf16 v[40:43], v[44:47], v[172:175], v[40:43]
	v_mfma_f32_16x16x32_bf16 v[44:47], v[60:63], v[172:175], v[56:59]
	v_mfma_f32_16x16x32_bf16 v[56:59], v[76:79], v[172:175], v[72:75]
	v_mfma_f32_16x16x32_bf16 v[60:63], v[92:95], v[172:175], v[88:91]
	v_mfma_f32_16x16x32_bf16 v[48:51], v[172:175], v[52:55], v[48:51]
	v_mfma_f32_16x16x32_bf16 v[52:55], v[172:175], v[68:71], v[64:67]
	v_mfma_f32_16x16x32_bf16 v[64:67], v[172:175], v[84:87], v[80:83]
	v_mfma_f32_16x16x32_bf16 v[68:71], v[172:175], v[100:103], v[96:99]
	s_waitcnt lgkmcnt(0)
	s_barrier
	ds_read_b128 v[160:163], v37 offset:30720
	ds_read_b128 v[164:167], v37 offset:31744
	ds_read_b128 v[72:75], v37 offset:32768
	ds_read_b128 v[76:79], v37 offset:34816
	ds_read_b128 v[80:83], v37 offset:36864
	ds_read_b128 v[84:87], v37 offset:38912
	ds_read_b128 v[88:91], v37 offset:40960
	ds_read_b128 v[92:95], v37 offset:43008
	ds_read_b128 v[96:99], v37 offset:45056
	ds_read_b128 v[100:103], v37 offset:47104
	ds_read_b128 v[168:171], v37 offset:49152
	ds_read_b128 v[172:175], v37 offset:51200
	ds_read_b128 v[184:187], v37 offset:53248
	ds_read_b128 v[188:191], v37 offset:54272
	ds_read_b128 v[202:205], v37 offset:55296
	ds_read_b128 v[206:209], v37 offset:56320
	s_add_i32 s46, s46, s54
	v_add_u32_e32 v39, s46, v38
	ds_read_b128 v[210:213], v39 offset:57344
	ds_read_b128 v[214:217], v39 offset:57360
	s_waitcnt lgkmcnt(15)
	v_mfma_f32_16x16x32_bf16 v[40:43], v[104:107], v[176:179], v[40:43]
	v_mfma_f32_16x16x32_bf16 v[44:47], v[120:123], v[176:179], v[44:47]
	v_mfma_f32_16x16x32_bf16 v[56:59], v[136:139], v[176:179], v[56:59]
	v_mfma_f32_16x16x32_bf16 v[60:63], v[152:155], v[176:179], v[60:63]
	v_mfma_f32_16x16x32_bf16 v[48:51], v[176:179], v[112:115], v[48:51]
	v_mfma_f32_16x16x32_bf16 v[52:55], v[176:179], v[128:131], v[52:55]
	v_mfma_f32_16x16x32_bf16 v[64:67], v[176:179], v[144:147], v[64:67]
	v_mfma_f32_16x16x32_bf16 v[68:71], v[176:179], v[160:163], v[68:71]
	v_mfma_f32_16x16x32_bf16 v[40:43], v[108:111], v[180:183], v[40:43]
	v_mfma_f32_16x16x32_bf16 v[44:47], v[124:127], v[180:183], v[44:47]
	v_mfma_f32_16x16x32_bf16 v[56:59], v[140:143], v[180:183], v[56:59]
	v_mfma_f32_16x16x32_bf16 v[60:63], v[156:159], v[180:183], v[60:63]
	v_mfma_f32_16x16x32_bf16 v[48:51], v[180:183], v[116:119], v[48:51]
	v_mfma_f32_16x16x32_bf16 v[52:55], v[180:183], v[132:135], v[52:55]
	v_mfma_f32_16x16x32_bf16 v[64:67], v[180:183], v[148:151], v[64:67]
	v_mfma_f32_16x16x32_bf16 v[68:71], v[180:183], v[164:167], v[68:71]
	ds_read_b128 v[104:107], v37 offset:33792
	ds_read_b128 v[108:111], v37 offset:35840
	ds_read_b128 v[112:115], v37 offset:37888
	ds_read_b128 v[116:119], v37 offset:39936
	ds_read_b128 v[120:123], v37 offset:41984
	ds_read_b128 v[124:127], v37 offset:44032
	ds_read_b128 v[128:131], v37 offset:46080
	ds_read_b128 v[132:135], v37 offset:48128
	s_waitcnt lgkmcnt(8)
	v_lshlrev_b32_e32 v37, 16, v210
	v_and_b32_e32 v39, 0xffff0000, v210
	v_lshlrev_b32_e32 v136, 16, v211
	v_and_b32_e32 v137, 0xffff0000, v211
	v_sub_f32_e32 v43, v137, v43
	v_sub_f32_e32 v42, v136, v42
	v_sub_f32_e32 v39, v39, v41
	v_sub_f32_e32 v37, v37, v40
	v_lshlrev_b32_e32 v40, 16, v212
	v_and_b32_e32 v41, 0xffff0000, v212
	v_lshlrev_b32_e32 v136, 16, v213
	v_and_b32_e32 v137, 0xffff0000, v213
	v_sub_f32_e32 v47, v137, v47
	v_sub_f32_e32 v46, v136, v46
	v_sub_f32_e32 v45, v41, v45
	v_sub_f32_e32 v44, v40, v44
	v_lshlrev_b32_e32 v40, 16, v214
	v_and_b32_e32 v41, 0xffff0000, v214
	v_lshlrev_b32_e32 v136, 16, v215
	v_and_b32_e32 v137, 0xffff0000, v215
	v_sub_f32_e32 v59, v137, v59
	v_sub_f32_e32 v58, v136, v58
	v_sub_f32_e32 v57, v41, v57
	v_sub_f32_e32 v56, v40, v56
	v_lshlrev_b32_e32 v40, 16, v216
	v_and_b32_e32 v41, 0xffff0000, v216
	v_lshlrev_b32_e32 v136, 16, v217
	v_and_b32_e32 v137, 0xffff0000, v217
	v_sub_f32_e32 v63, v137, v63
	v_sub_f32_e32 v62, v136, v62
	v_sub_f32_e32 v61, v41, v61
	v_sub_f32_e32 v60, v40, v60
	v_pk_mul_f32 v[22:23], v[22:23], v[36:37] op_sel_hi:[1,0]
	v_pk_mul_f32 v[20:21], v[20:21], v[36:37] op_sel_hi:[1,0]
	v_pk_mul_f32 v[30:31], v[30:31], v[36:37] op_sel_hi:[1,0]
	v_pk_mul_f32 v[28:29], v[28:29], v[36:37] op_sel_hi:[1,0]
	v_pk_mul_f32 v[26:27], v[26:27], v[36:37] op_sel_hi:[1,0]
	v_pk_mul_f32 v[24:25], v[24:25], v[36:37] op_sel_hi:[1,0]
	v_pk_mul_f32 v[18:19], v[18:19], v[36:37] op_sel_hi:[1,0]
	v_pk_mul_f32 v[16:17], v[16:17], v[36:37] op_sel_hi:[1,0]
	v_pk_mul_f32 v[14:15], v[14:15], v[36:37] op_sel_hi:[1,0]
	v_pk_mul_f32 v[12:13], v[12:13], v[36:37] op_sel_hi:[1,0]
	v_pk_mul_f32 v[10:11], v[10:11], v[36:37] op_sel_hi:[1,0]
	v_pk_mul_f32 v[8:9], v[8:9], v[36:37] op_sel_hi:[1,0]
	v_pk_mul_f32 v[6:7], v[6:7], v[36:37] op_sel_hi:[1,0]
	v_pk_mul_f32 v[4:5], v[4:5], v[36:37] op_sel_hi:[1,0]
	v_pk_mul_f32 v[2:3], v[2:3], v[36:37] op_sel_hi:[1,0]
	v_pk_mul_f32 v[0:1], v[0:1], v[36:37] op_sel_hi:[1,0]
	v_cvt_pk_bf16_f32 v40, v37, v39
	v_cvt_pk_bf16_f32 v41, v42, v43
	v_cvt_pk_bf16_f32 v42, v44, v45
	v_cvt_pk_bf16_f32 v43, v46, v47
	v_cvt_pk_bf16_f32 v44, v56, v57
	v_cvt_pk_bf16_f32 v45, v58, v59
	v_cvt_pk_bf16_f32 v46, v60, v61
	v_cvt_pk_bf16_f32 v47, v62, v63
	v_mfma_f32_16x16x32_bf16 v[20:23], v[72:75], v[40:43], v[20:23]
	v_mfma_f32_16x16x32_bf16 v[28:31], v[76:79], v[40:43], v[28:31]
	v_mfma_f32_16x16x32_bf16 v[24:27], v[80:83], v[40:43], v[24:27]
	v_mfma_f32_16x16x32_bf16 v[16:19], v[84:87], v[40:43], v[16:19]
	v_mfma_f32_16x16x32_bf16 v[12:15], v[88:91], v[40:43], v[12:15]
	v_mfma_f32_16x16x32_bf16 v[8:11], v[92:95], v[40:43], v[8:11]
	v_mfma_f32_16x16x32_bf16 v[4:7], v[96:99], v[40:43], v[4:7]
	v_mfma_f32_16x16x32_bf16 v[0:3], v[100:103], v[40:43], v[0:3]
	v_mfma_f32_16x16x32_bf16 v[48:51], v[40:43], v[168:171], v[48:51]
	v_mfma_f32_16x16x32_bf16 v[52:55], v[40:43], v[172:175], v[52:55]
	v_mfma_f32_16x16x32_bf16 v[56:59], v[40:43], v[184:187], v[64:67]
	v_mfma_f32_16x16x32_bf16 v[40:43], v[40:43], v[202:205], v[68:71]
	s_waitcnt lgkmcnt(0)
	v_mfma_f32_16x16x32_bf16 v[20:23], v[104:107], v[44:47], v[20:23]
	v_mfma_f32_16x16x32_bf16 v[28:31], v[108:111], v[44:47], v[28:31]
	v_mfma_f32_16x16x32_bf16 v[24:27], v[112:115], v[44:47], v[24:27]
	v_mfma_f32_16x16x32_bf16 v[16:19], v[116:119], v[44:47], v[16:19]
	v_mfma_f32_16x16x32_bf16 v[12:15], v[120:123], v[44:47], v[12:15]
	v_mfma_f32_16x16x32_bf16 v[8:11], v[124:127], v[44:47], v[8:11]
	v_mfma_f32_16x16x32_bf16 v[4:7], v[128:131], v[44:47], v[4:7]
	v_mfma_f32_16x16x32_bf16 v[0:3], v[132:135], v[44:47], v[0:3]
	v_mfma_f32_16x16x32_bf16 v[56:59], v[44:47], v[188:191], v[56:59]
	v_mfma_f32_16x16x32_bf16 v[40:43], v[44:47], v[206:209], v[40:43]
	v_lshl_add_u64 v[36:37], v[34:35], 0, s[88:89]
	s_mov_b32 s46, 0xec00000
	v_add_co_u32_e32 v46, vcc, s46, v36
	v_cvt_pk_bf16_f32 v44, v48, v49
	v_cvt_pk_bf16_f32 v45, v50, v51
	v_addc_co_u32_e32 v47, vcc, 0, v37, vcc
	s_mov_b32 s46, 0xec08000
	global_store_dwordx2 v[46:47], v[44:45], off
	v_add_co_u32_e32 v46, vcc, s46, v36
	v_cvt_pk_bf16_f32 v44, v52, v53
	v_cvt_pk_bf16_f32 v45, v54, v55
	v_addc_co_u32_e32 v47, vcc, 0, v37, vcc
	s_mov_b32 s46, 0xec10000
	global_store_dwordx2 v[46:47], v[44:45], off
	v_add_co_u32_e32 v46, vcc, s46, v36
	v_cvt_pk_bf16_f32 v44, v56, v57
	s_nop 0
	v_addc_co_u32_e32 v47, vcc, 0, v37, vcc
	v_add_co_u32_e32 v36, vcc, 0xec18000, v36
	v_cvt_pk_bf16_f32 v45, v58, v59
	v_cvt_pk_bf16_f32 v40, v40, v41
	v_cvt_pk_bf16_f32 v41, v42, v43
	v_addc_co_u32_e32 v37, vcc, 0, v37, vcc
	global_store_dwordx2 v[46:47], v[44:45], off
	global_store_dwordx2 v[36:37], v[40:41], off
	s_waitcnt vmcnt(4) lgkmcnt(0)
	s_branch .LBB0_710
